# attention epilogue store tail: eight LDS transpose reads issued together with counted waits in front of the stores
# baseline (speedup 1.0000x reference)
; #define LAS __attribute__((address_space(3)))
; __device__ __forceinline__ unsigned cvt_pk_bf16(float lo, float hi) { unsigned r; asm volatile("v_cvt_pk_bf16_f32 %0, %1, %2" : "=v"(r) : "v"(lo), "v"(hi)); return r; }
; __device__ __forceinline__ float xhalf_sum(float v) { auto rr = __builtin_amdgcn_permlane32_swap(__float_as_uint(v), __float_as_uint(v), false, false); return __uint_as_float(rr[0]) + __uint_as_float(rr[1]); }
; __device__ __forceinline__ void attn_phase(const Args& A, LAS unsigned char* lds, int vcu, int G, const int tid) {
;     ...
;         if (c == 0) {
;             float ss = 0.f;
; #pragma unroll
;             for (int i = 0; i < 4; ++i)
; #pragma unroll
;                 for (int r = 0; r < 16; ++r) { const float d = o[i][r] * inv - scr[(i * 16 + r) * 64 + lane]; o[i][r] = d; ss += d * d; }
;             ss = xhalf_sum(ss);
;             const float rn = (1.0f - LAMBDA_INIT) / sqrtf(ss * (1.0f / 128.0f) + RMS_EPS);
;             int ln = lane; asm volatile("" : "+v"(ln));
;             const int er32 = ln & 31, ehi = ln >> 5;
;             LAS unsigned char* stg = lds + 65536 + qi * (32 * 272);
;             const float* sg = A.in[I_SUBG] + 4 * ehi;
; #pragma unroll
;             for (int i = 0; i < 4; ++i)
; #pragma unroll
;                 for (int rq = 0; rq < 4; ++rq) { const f32x4 gq = *(const f32x4*)(sg + 32 * i + 8 * rq);
;                     u32x2 w; w.x = cvt_pk_bf16(o[i][4 * rq] * rn * gq[0], o[i][4 * rq + 1] * rn * gq[1]); w.y = cvt_pk_bf16(o[i][4 * rq + 2] * rn * gq[2], o[i][4 * rq + 3] * rn * gq[3]);
;                     *(LAS u32x2*)(stg + er32 * 272 + (32 * i + 8 * rq + 4 * ehi) * 2) = w; }
.LBB0_963:
	s_and_b64 vcc, exec, s[4:5]
	s_waitcnt vmcnt(0) lgkmcnt(0)
	s_barrier
	s_cbranch_vccnz .LBB0_839
	ds_read2st64_b32 v[34:35], v210 offset1:1
	ds_read2st64_b32 v[36:37], v210 offset0:2 offset1:3
	ds_read2st64_b32 v[38:39], v210 offset0:4 offset1:5
	ds_read2st64_b32 v[40:41], v210 offset0:6 offset1:7
	s_ashr_i32 s39, s38, 31
	s_waitcnt lgkmcnt(3)
	v_fma_f32 v33, v80, v32, -v34
	v_fma_f32 v46, v81, v32, -v35
	ds_read2st64_b32 v[34:35], v210 offset0:8 offset1:9
	s_waitcnt lgkmcnt(3)
	v_fma_f32 v48, v82, v32, -v36
	v_fma_f32 v49, v83, v32, -v37
	s_waitcnt lgkmcnt(2)
	v_fma_f32 v50, v84, v32, -v38
	v_fma_f32 v51, v85, v32, -v39
	s_waitcnt lgkmcnt(1)
	v_fma_f32 v52, v86, v32, -v40
	v_fma_f32 v53, v87, v32, -v41
	ds_read2st64_b32 v[36:37], v210 offset0:10 offset1:11
	ds_read2st64_b32 v[38:39], v210 offset0:12 offset1:13
	ds_read2st64_b32 v[40:41], v210 offset0:14 offset1:15
	s_waitcnt lgkmcnt(3)
	v_fma_f32 v54, v88, v32, -v34
	v_fma_f32 v55, v89, v32, -v35
	ds_read2st64_b32 v[34:35], v210 offset0:16 offset1:17
	s_waitcnt lgkmcnt(3)
	v_fma_f32 v56, v90, v32, -v36
	v_fma_f32 v57, v91, v32, -v37
	s_waitcnt lgkmcnt(2)
	v_fma_f32 v58, v92, v32, -v38
	v_fma_f32 v59, v93, v32, -v39
	s_waitcnt lgkmcnt(1)
	v_fma_f32 v60, v94, v32, -v40
	v_fma_f32 v61, v95, v32, -v41
	ds_read2st64_b32 v[36:37], v210 offset0:18 offset1:19
	ds_read2st64_b32 v[38:39], v210 offset0:20 offset1:21
	ds_read2st64_b32 v[40:41], v210 offset0:22 offset1:23
	s_waitcnt lgkmcnt(3)
	v_fma_f32 v62, v64, v32, -v34
	v_fma_f32 v63, v65, v32, -v35
	ds_read2st64_b32 v[34:35], v210 offset0:24 offset1:25
	s_waitcnt lgkmcnt(3)
	v_fma_f32 v64, v66, v32, -v36
	v_fma_f32 v65, v67, v32, -v37
	s_waitcnt lgkmcnt(2)
	v_fma_f32 v66, v68, v32, -v38
	v_fma_f32 v67, v69, v32, -v39
	s_waitcnt lgkmcnt(1)
	v_fma_f32 v68, v70, v32, -v40
	v_fma_f32 v69, v71, v32, -v41
	ds_read2st64_b32 v[36:37], v210 offset0:26 offset1:27
	ds_read2st64_b32 v[38:39], v210 offset0:28 offset1:29
	ds_read2st64_b32 v[40:41], v210 offset0:30 offset1:31
	v_mul_f32_e32 v47, v46, v46
	v_fmac_f32_e32 v47, v33, v33
	v_fmac_f32_e32 v47, v48, v48
	v_fmac_f32_e32 v47, v49, v49
	s_waitcnt lgkmcnt(3)
	v_fma_f32 v70, v72, v32, -v34
	v_fma_f32 v71, v73, v32, -v35
	ds_read2st64_b32 v[34:35], v210 offset0:32 offset1:33
	v_fmac_f32_e32 v47, v50, v50
	s_waitcnt lgkmcnt(3)
	v_fma_f32 v72, v74, v32, -v36
	v_fma_f32 v73, v75, v32, -v37
	s_waitcnt lgkmcnt(2)
	v_fma_f32 v74, v76, v32, -v38
	v_fma_f32 v75, v77, v32, -v39
	s_waitcnt lgkmcnt(1)
	v_fma_f32 v76, v78, v32, -v40
	v_fma_f32 v77, v79, v32, -v41
	ds_read2st64_b32 v[36:37], v210 offset0:34 offset1:35
	ds_read2st64_b32 v[38:39], v210 offset0:36 offset1:37
	ds_read2st64_b32 v[40:41], v210 offset0:38 offset1:39
	v_fmac_f32_e32 v47, v51, v51
	v_fmac_f32_e32 v47, v52, v52
	v_fmac_f32_e32 v47, v53, v53
	v_fmac_f32_e32 v47, v54, v54
	s_waitcnt lgkmcnt(3)
	v_fma_f32 v78, v16, v32, -v34
	v_fma_f32 v79, v17, v32, -v35
	ds_read2st64_b32 v[16:17], v210 offset0:40 offset1:41
	v_fmac_f32_e32 v47, v55, v55
	s_waitcnt lgkmcnt(3)
	v_fma_f32 v80, v18, v32, -v36
	v_fma_f32 v81, v19, v32, -v37
	s_waitcnt lgkmcnt(2)
	v_fma_f32 v82, v20, v32, -v38
	v_fma_f32 v83, v21, v32, -v39
	s_waitcnt lgkmcnt(1)
	v_fma_f32 v84, v22, v32, -v40
	v_fma_f32 v85, v23, v32, -v41
	ds_read2st64_b32 v[18:19], v210 offset0:42 offset1:43
	ds_read2st64_b32 v[20:21], v210 offset0:44 offset1:45
	ds_read2st64_b32 v[22:23], v210 offset0:46 offset1:47
	v_fmac_f32_e32 v47, v56, v56
	v_fmac_f32_e32 v47, v57, v57
	v_fmac_f32_e32 v47, v58, v58
	v_mov_b32_e32 v92, v201
	v_fmac_f32_e32 v47, v59, v59
	s_waitcnt lgkmcnt(3)
	v_fma_f32 v86, v24, v32, -v16
	v_fma_f32 v87, v25, v32, -v17
	s_waitcnt lgkmcnt(2)
	v_fma_f32 v88, v26, v32, -v18
	v_fma_f32 v89, v27, v32, -v19
	s_waitcnt lgkmcnt(1)
	v_fma_f32 v90, v28, v32, -v20
	v_fma_f32 v91, v29, v32, -v21
	ds_read2st64_b32 v[24:25], v210 offset0:48 offset1:49
	ds_read2st64_b32 v[26:27], v210 offset0:50 offset1:51
	ds_read2st64_b32 v[28:29], v210 offset0:52 offset1:53
	ds_read2st64_b32 v[34:35], v210 offset0:54 offset1:55
	ds_read2st64_b32 v[36:37], v210 offset0:56 offset1:57
	ds_read2st64_b32 v[38:39], v210 offset0:58 offset1:59
	ds_read2st64_b32 v[40:41], v210 offset0:60 offset1:61
	ds_read2st64_b32 v[42:43], v210 offset0:62 offset1:63
	v_fmac_f32_e32 v47, v60, v60
	v_ashrrev_i32_e32 v16, 3, v92
	v_and_b32_e32 v44, -4, v16
	v_fmac_f32_e32 v47, v61, v61
	v_ashrrev_i32_e32 v45, 31, v44
	v_fmac_f32_e32 v47, v62, v62
	v_lshl_add_u64 v[16:17], v[44:45], 2, s[76:77]
	v_fmac_f32_e32 v47, v63, v63
	global_load_dwordx4 v[18:21], v[16:17], off
	global_load_dwordx4 v[96:99], v[16:17], off offset:32
	global_load_dwordx4 v[100:103], v[16:17], off offset:64
	global_load_dwordx4 v[104:107], v[16:17], off offset:96
	global_load_dwordx4 v[108:111], v[16:17], off offset:128
	global_load_dwordx4 v[112:115], v[16:17], off offset:160
	global_load_dwordx4 v[116:119], v[16:17], off offset:192
	global_load_dwordx4 v[120:123], v[16:17], off offset:224
	global_load_dwordx4 v[124:127], v[16:17], off offset:256
	global_load_dwordx4 v[128:131], v[16:17], off offset:288
	global_load_dwordx4 v[132:135], v[16:17], off offset:320
	global_load_dwordx4 v[136:139], v[16:17], off offset:352
	global_load_dwordx4 v[140:143], v[16:17], off offset:384
	global_load_dwordx4 v[144:147], v[16:17], off offset:416
	global_load_dwordx4 v[148:151], v[16:17], off offset:448
	global_load_dwordx4 v[152:155], v[16:17], off offset:480
	v_fmac_f32_e32 v47, v64, v64
	v_fmac_f32_e32 v47, v65, v65
	v_fmac_f32_e32 v47, v66, v66
	v_fmac_f32_e32 v47, v67, v67
	v_fmac_f32_e32 v47, v68, v68
	v_fmac_f32_e32 v47, v69, v69
	v_fmac_f32_e32 v47, v70, v70
	v_fmac_f32_e32 v47, v71, v71
	v_fmac_f32_e32 v47, v72, v72
	v_fmac_f32_e32 v47, v73, v73
	v_fmac_f32_e32 v47, v74, v74
	v_fmac_f32_e32 v47, v75, v75
	v_fmac_f32_e32 v47, v76, v76
	v_fmac_f32_e32 v47, v77, v77
	v_fmac_f32_e32 v47, v78, v78
	v_fmac_f32_e32 v47, v79, v79
	v_fmac_f32_e32 v47, v80, v80
	v_fmac_f32_e32 v47, v81, v81
	v_fmac_f32_e32 v47, v82, v82
	v_fmac_f32_e32 v47, v83, v83
	v_fmac_f32_e32 v47, v84, v84
	v_fmac_f32_e32 v47, v85, v85
	v_fmac_f32_e32 v47, v86, v86
	v_fmac_f32_e32 v47, v87, v87
	v_fmac_f32_e32 v47, v88, v88
	v_fmac_f32_e32 v47, v89, v89
	v_fmac_f32_e32 v47, v90, v90
	v_fmac_f32_e32 v47, v91, v91
	s_waitcnt lgkmcnt(8)
; #define LAS __attribute__((address_space(3)))
; __device__ __forceinline__ unsigned cvt_pk_bf16(float lo, float hi) { unsigned r; asm volatile("v_cvt_pk_bf16_f32 %0, %1, %2" : "=v"(r) : "v"(lo), "v"(hi)); return r; }
; __device__ __forceinline__ float xhalf_sum(float v) { auto rr = __builtin_amdgcn_permlane32_swap(__float_as_uint(v), __float_as_uint(v), false, false); return __uint_as_float(rr[0]) + __uint_as_float(rr[1]); }
; __device__ __forceinline__ void attn_phase(const Args& A, LAS unsigned char* lds, int vcu, int G, const int tid) {
;     ...
;                 for (int r = 0; r < 16; ++r) { const float d = o[i][r] * inv - scr[(i * 16 + r) * 64 + lane]; o[i][r] = d; ss += d * d; }
;             ss = xhalf_sum(ss);
;             const float rn = (1.0f - LAMBDA_INIT) / sqrtf(ss * (1.0f / 128.0f) + RMS_EPS);
;             int ln = lane; asm volatile("" : "+v"(ln));
;             const int er32 = ln & 31, ehi = ln >> 5;
;             LAS unsigned char* stg = lds + 65536 + qi * (32 * 272);
;             const float* sg = A.in[I_SUBG] + 4 * ehi;
; #pragma unroll
;             for (int i = 0; i < 4; ++i)
; #pragma unroll
;                 for (int rq = 0; rq < 4; ++rq) { const f32x4 gq = *(const f32x4*)(sg + 32 * i + 8 * rq);
;                     u32x2 w; w.x = cvt_pk_bf16(o[i][4 * rq] * rn * gq[0], o[i][4 * rq + 1] * rn * gq[1]); w.y = cvt_pk_bf16(o[i][4 * rq + 2] * rn * gq[2], o[i][4 * rq + 3] * rn * gq[3]);
;                     *(LAS u32x2*)(stg + er32 * 272 + (32 * i + 8 * rq + 4 * ehi) * 2) = w; }
	v_fma_f32 v22, v30, v32, -v22
	v_fmac_f32_e32 v47, v22, v22
	v_fma_f32 v23, v31, v32, -v23
	v_fmac_f32_e32 v47, v23, v23
	s_waitcnt lgkmcnt(7)
	v_fma_f32 v24, v0, v32, -v24
	v_fmac_f32_e32 v47, v24, v24
	v_fma_f32 v25, v1, v32, -v25
	v_fmac_f32_e32 v47, v25, v25
	s_waitcnt lgkmcnt(6)
	v_fma_f32 v26, v2, v32, -v26
	v_fmac_f32_e32 v47, v26, v26
	v_fma_f32 v27, v3, v32, -v27
	v_fmac_f32_e32 v47, v27, v27
	s_waitcnt lgkmcnt(5)
	v_fma_f32 v28, v4, v32, -v28
	v_fmac_f32_e32 v47, v28, v28
	v_fma_f32 v29, v5, v32, -v29
	v_fmac_f32_e32 v47, v29, v29
	s_waitcnt lgkmcnt(4)
	v_fma_f32 v6, v6, v32, -v34
	v_fmac_f32_e32 v47, v6, v6
	v_fma_f32 v7, v7, v32, -v35
	v_fmac_f32_e32 v47, v7, v7
	s_waitcnt lgkmcnt(3)
	v_fma_f32 v8, v8, v32, -v36
	v_fmac_f32_e32 v47, v8, v8
	v_fma_f32 v9, v9, v32, -v37
	v_fmac_f32_e32 v47, v9, v9
	s_waitcnt lgkmcnt(2)
	v_fma_f32 v10, v10, v32, -v38
	v_fmac_f32_e32 v47, v10, v10
	v_fma_f32 v11, v11, v32, -v39
	v_fmac_f32_e32 v47, v11, v11
	s_waitcnt lgkmcnt(1)
	v_fma_f32 v30, v12, v32, -v40
	v_fmac_f32_e32 v47, v30, v30
	v_fma_f32 v13, v13, v32, -v41
	v_fmac_f32_e32 v47, v13, v13
	s_waitcnt lgkmcnt(0)
	v_fma_f32 v14, v14, v32, -v42
	v_fmac_f32_e32 v47, v14, v14
	v_fma_f32 v15, v15, v32, -v43
	v_fmac_f32_e32 v47, v15, v15
	v_mov_b32_e32 v0, v47
	s_nop 1
	v_permlane32_swap_b32_e32 v47, v0
	v_add_f32_e32 v0, v47, v0
	v_fmamk_f32 v0, v0, 0x3c000000, v215
	v_mul_f32_e32 v1, 0x4f800000, v0
	v_cmp_gt_f32_e32 vcc, s9, v0
	v_and_b32_e32 v12, 31, v92
	v_mul_u32_u24_e32 v12, 0x110, v12
	v_cndmask_b32_e32 v0, v0, v1, vcc
	v_sqrt_f32_e32 v1, v0
	s_movk_i32 s12, 0x4000
	v_add_u32_e32 v2, -1, v1
	v_fma_f32 v3, -v2, v1, v0
	v_cmp_ge_f32_e64 s[4:5], 0, v3
	v_add_u32_e32 v3, 1, v1
	s_nop 0
	v_cndmask_b32_e64 v2, v1, v2, s[4:5]
	v_fma_f32 v1, -v3, v1, v0
	v_cmp_lt_f32_e64 s[4:5], 0, v1
	s_nop 1
	v_cndmask_b32_e64 v1, v2, v3, s[4:5]
	v_mul_f32_e32 v2, 0x37800000, v1
	v_cndmask_b32_e32 v1, v1, v2, vcc
	v_cmp_class_f32_e32 vcc, v0, v202
	s_movk_i32 s4, 0x110
	s_movk_i32 s5, 0x2000
	v_cndmask_b32_e32 v0, v1, v0, vcc
	v_div_scale_f32 v1, s[2:3], v0, v0, s63
	v_rcp_f32_e32 v2, v1
	s_lshl_b64 s[2:3], s[38:39], 11
	s_add_u32 s13, s18, s2
	s_addc_u32 s14, s19, s3
	v_fma_f32 v3, -v1, v2, 1.0
	v_fmac_f32_e32 v2, v3, v2
	v_div_scale_f32 v3, vcc, s63, v0, s63
	v_mul_f32_e32 v4, v3, v2
	v_fma_f32 v5, -v1, v4, v3
	v_fmac_f32_e32 v4, v5, v2
	v_fma_f32 v1, -v1, v4, v3
	v_div_fmas_f32 v1, v1, v2, v4
	v_div_fixup_f32 v31, v1, v0, s63
	v_mul_f32_e32 v0, v33, v31
	v_mul_f32_e32 v1, v46, v31
	s_waitcnt vmcnt(0)
	v_mul_f32_e32 v0, v18, v0
	v_mul_f32_e32 v1, v19, v1
	v_cvt_pk_bf16_f32 v4, v0, v1
	v_mul_f32_e32 v0, v48, v31
	v_mul_f32_e32 v1, v49, v31
	v_mul_f32_e32 v0, v20, v0
	v_mul_f32_e32 v1, v21, v1
	v_cvt_pk_bf16_f32 v5, v0, v1
	v_lshlrev_b32_e32 v18, 1, v44
	v_add3_u32 v18, s60, v12, v18
	ds_write_b64 v18, v[4:5]
	v_mul_f32_e32 v4, v50, v31
	v_mul_f32_e32 v12, v54, v31
	v_mul_f32_e32 v19, v55, v31
	v_mul_f32_e32 v20, v56, v31
	v_mul_f32_e32 v21, v57, v31
	v_mul_f32_e32 v6, v6, v31
	v_mul_f32_e32 v7, v7, v31
	s_lshl_b64 s[2:3], s[36:37], 1
	s_add_u32 s2, s13, s2
	s_addc_u32 s3, s14, s3
	v_mov_b64_e32 v[0:1], v[96:97]
	v_mov_b64_e32 v[2:3], v[98:99]
	v_mul_f32_e32 v0, v0, v4
	v_mul_f32_e32 v4, v51, v31
	v_mul_f32_e32 v1, v1, v4
	v_cvt_pk_bf16_f32 v4, v0, v1
	v_mul_f32_e32 v0, v52, v31
	v_mul_f32_e32 v1, v53, v31
	v_mul_f32_e32 v0, v2, v0
	v_mul_f32_e32 v1, v3, v1
	v_cvt_pk_bf16_f32 v5, v0, v1
	ds_write_b64 v18, v[4:5] offset:16
	v_mov_b64_e32 v[0:1], v[100:101]
	v_mov_b64_e32 v[2:3], v[102:103]
	v_mul_f32_e32 v0, v12, v0
	v_mul_f32_e32 v1, v19, v1
	v_mul_f32_e32 v2, v20, v2
	v_mul_f32_e32 v3, v21, v3
	v_cvt_pk_bf16_f32 v4, v0, v1
	v_cvt_pk_bf16_f32 v5, v2, v3
	v_mul_f32_e32 v12, v58, v31
	v_mul_f32_e32 v19, v59, v31
	v_mul_f32_e32 v20, v60, v31
	v_mul_f32_e32 v21, v61, v31
	ds_write_b64 v18, v[4:5] offset:32
	v_mov_b64_e32 v[0:1], v[104:105]
	v_mov_b64_e32 v[2:3], v[106:107]
	v_mul_f32_e32 v0, v12, v0
	v_mul_f32_e32 v1, v19, v1
	v_mul_f32_e32 v2, v20, v2
	v_mul_f32_e32 v3, v21, v3
	v_cvt_pk_bf16_f32 v4, v0, v1
	v_cvt_pk_bf16_f32 v5, v2, v3
	v_mul_f32_e32 v12, v62, v31
	v_mul_f32_e32 v19, v63, v31
	v_mul_f32_e32 v20, v64, v31
	v_mul_f32_e32 v21, v65, v31
	ds_write_b64 v18, v[4:5] offset:48
	v_mov_b64_e32 v[0:1], v[108:109]
	v_mov_b64_e32 v[2:3], v[110:111]
	v_mul_f32_e32 v0, v12, v0
	v_mul_f32_e32 v1, v19, v1
	v_mul_f32_e32 v2, v20, v2
	v_mul_f32_e32 v3, v21, v3
	v_cvt_pk_bf16_f32 v4, v0, v1
	v_cvt_pk_bf16_f32 v5, v2, v3
	v_mul_f32_e32 v12, v66, v31
	v_mul_f32_e32 v19, v67, v31
	v_mul_f32_e32 v20, v68, v31
	v_mul_f32_e32 v21, v69, v31
	ds_write_b64 v18, v[4:5] offset:64
	v_mov_b64_e32 v[0:1], v[112:113]
	v_mov_b64_e32 v[2:3], v[114:115]
	v_mul_f32_e32 v0, v12, v0
	v_mul_f32_e32 v1, v19, v1
	v_mul_f32_e32 v2, v20, v2
	v_mul_f32_e32 v3, v21, v3
	v_cvt_pk_bf16_f32 v4, v0, v1
	v_cvt_pk_bf16_f32 v5, v2, v3
	v_mul_f32_e32 v12, v70, v31
	v_mul_f32_e32 v19, v71, v31
	v_mul_f32_e32 v20, v72, v31
	v_mul_f32_e32 v21, v73, v31
	ds_write_b64 v18, v[4:5] offset:80
	v_mov_b64_e32 v[0:1], v[116:117]
	v_mov_b64_e32 v[2:3], v[118:119]
	v_mul_f32_e32 v0, v12, v0
	v_mul_f32_e32 v1, v19, v1
	v_mul_f32_e32 v2, v20, v2
	v_mul_f32_e32 v3, v21, v3
	v_cvt_pk_bf16_f32 v4, v0, v1
	v_cvt_pk_bf16_f32 v5, v2, v3
	v_mul_f32_e32 v12, v74, v31
; #define LAS __attribute__((address_space(3)))
; __device__ __forceinline__ unsigned cvt_pk_bf16(float lo, float hi) { unsigned r; asm volatile("v_cvt_pk_bf16_f32 %0, %1, %2" : "=v"(r) : "v"(lo), "v"(hi)); return r; }
; __device__ __forceinline__ void attn_phase(const Args& A, LAS unsigned char* lds, int vcu, int G, const int tid) {
;     ...
;             for (int i = 0; i < 4; ++i)
; #pragma unroll
;                 for (int rq = 0; rq < 4; ++rq) { const f32x4 gq = *(const f32x4*)(sg + 32 * i + 8 * rq);
;                     u32x2 w; w.x = cvt_pk_bf16(o[i][4 * rq] * rn * gq[0], o[i][4 * rq + 1] * rn * gq[1]); w.y = cvt_pk_bf16(o[i][4 * rq + 2] * rn * gq[2], o[i][4 * rq + 3] * rn * gq[3]);
;                     *(LAS u32x2*)(stg + er32 * 272 + (32 * i + 8 * rq + 4 * ehi) * 2) = w; }
;             asm volatile("s_waitcnt lgkmcnt(0)" ::: "memory");
;             bf16_t* obase = AO + (size_t)(qrow - r32) * DM + h * 128;
; #pragma unroll
;             for (int k = 0; k < 8; ++k) { const int row = 4 * k + (ln >> 4), ch = ln & 15;
;                 const u32x4 v = *(const LAS u32x4*)(stg + row * 272 + ch * 16);
;                 *(u32x4*)(obase + (size_t)row * DM + ch * 8) = v;
;                 if (k & 1) asm volatile("" ::: "memory"); }
	v_mul_f32_e32 v19, v75, v31
	v_mul_f32_e32 v20, v76, v31
	v_mul_f32_e32 v21, v77, v31
	ds_write_b64 v18, v[4:5] offset:96
	v_mov_b64_e32 v[0:1], v[120:121]
	v_mov_b64_e32 v[2:3], v[122:123]
	v_mul_f32_e32 v0, v12, v0
	v_mul_f32_e32 v1, v19, v1
	v_mul_f32_e32 v2, v20, v2
	v_mul_f32_e32 v3, v21, v3
	v_cvt_pk_bf16_f32 v4, v0, v1
	v_cvt_pk_bf16_f32 v5, v2, v3
	v_mul_f32_e32 v12, v78, v31
	v_mul_f32_e32 v19, v79, v31
	v_mul_f32_e32 v20, v80, v31
	v_mul_f32_e32 v21, v81, v31
	ds_write_b64 v18, v[4:5] offset:112
	v_mov_b64_e32 v[0:1], v[124:125]
	v_mov_b64_e32 v[2:3], v[126:127]
	v_mul_f32_e32 v0, v12, v0
	v_mul_f32_e32 v1, v19, v1
	v_mul_f32_e32 v2, v20, v2
	v_mul_f32_e32 v3, v21, v3
	v_cvt_pk_bf16_f32 v4, v0, v1
	v_cvt_pk_bf16_f32 v5, v2, v3
	v_mul_f32_e32 v12, v82, v31
	v_mul_f32_e32 v19, v83, v31
	v_mul_f32_e32 v20, v84, v31
	v_mul_f32_e32 v21, v85, v31
	ds_write_b64 v18, v[4:5] offset:128
	v_mov_b64_e32 v[0:1], v[128:129]
	v_mov_b64_e32 v[2:3], v[130:131]
	v_mul_f32_e32 v0, v12, v0
	v_mul_f32_e32 v1, v19, v1
	v_mul_f32_e32 v2, v20, v2
	v_mul_f32_e32 v3, v21, v3
	v_cvt_pk_bf16_f32 v4, v0, v1
	v_cvt_pk_bf16_f32 v5, v2, v3
	v_mul_f32_e32 v12, v86, v31
	v_mul_f32_e32 v19, v87, v31
	v_mul_f32_e32 v20, v88, v31
	v_mul_f32_e32 v21, v89, v31
	ds_write_b64 v18, v[4:5] offset:144
	v_mov_b64_e32 v[0:1], v[132:133]
	v_mov_b64_e32 v[2:3], v[134:135]
	v_mul_f32_e32 v0, v12, v0
	v_mul_f32_e32 v1, v19, v1
	v_mul_f32_e32 v2, v20, v2
	v_mul_f32_e32 v3, v21, v3
	v_cvt_pk_bf16_f32 v4, v0, v1
	v_cvt_pk_bf16_f32 v5, v2, v3
	v_mul_f32_e32 v12, v90, v31
	v_mul_f32_e32 v19, v91, v31
	v_mul_f32_e32 v20, v22, v31
	v_mul_f32_e32 v21, v23, v31
	ds_write_b64 v18, v[4:5] offset:160
	v_mov_b64_e32 v[0:1], v[136:137]
	v_mov_b64_e32 v[2:3], v[138:139]
	v_mul_f32_e32 v0, v12, v0
	v_mul_f32_e32 v1, v19, v1
	v_mul_f32_e32 v2, v20, v2
	v_mul_f32_e32 v3, v21, v3
	v_cvt_pk_bf16_f32 v4, v0, v1
	v_cvt_pk_bf16_f32 v5, v2, v3
	v_mul_f32_e32 v12, v24, v31
	v_mul_f32_e32 v19, v25, v31
	v_mul_f32_e32 v20, v26, v31
	v_mul_f32_e32 v21, v27, v31
	ds_write_b64 v18, v[4:5] offset:176
	v_mov_b64_e32 v[0:1], v[140:141]
	v_mov_b64_e32 v[2:3], v[142:143]
	v_mul_f32_e32 v0, v12, v0
	v_mul_f32_e32 v1, v19, v1
	v_mul_f32_e32 v2, v20, v2
	v_mul_f32_e32 v3, v21, v3
	v_cvt_pk_bf16_f32 v4, v0, v1
	v_cvt_pk_bf16_f32 v5, v2, v3
	v_mul_f32_e32 v12, v28, v31
	v_mul_f32_e32 v19, v29, v31
	ds_write_b64 v18, v[4:5] offset:192
	v_mov_b64_e32 v[0:1], v[144:145]
	v_mov_b64_e32 v[2:3], v[146:147]
	v_mul_f32_e32 v0, v12, v0
	v_mul_f32_e32 v1, v19, v1
	v_mul_f32_e32 v2, v6, v2
	v_mul_f32_e32 v3, v7, v3
	v_cvt_pk_bf16_f32 v4, v0, v1
	v_cvt_pk_bf16_f32 v5, v2, v3
	v_mul_f32_e32 v6, v8, v31
	v_mul_f32_e32 v7, v9, v31
	v_mul_f32_e32 v8, v10, v31
	v_mul_f32_e32 v9, v11, v31
	ds_write_b64 v18, v[4:5] offset:208
	v_mul_f32_e32 v19, v15, v31
	v_mov_b64_e32 v[0:1], v[148:149]
	v_mov_b64_e32 v[2:3], v[150:151]
	v_mul_f32_e32 v0, v6, v0
	v_mul_f32_e32 v1, v7, v1
	v_mul_f32_e32 v2, v8, v2
	v_mul_f32_e32 v3, v9, v3
	v_cvt_pk_bf16_f32 v4, v0, v1
	v_cvt_pk_bf16_f32 v5, v2, v3
	v_ashrrev_i32_e32 v8, 4, v92
	v_lshlrev_b32_e32 v6, 4, v92
	v_mov_b32_e32 v7, v191
	v_and_b32_e32 v6, 0xf0, v6
	v_mul_lo_u32 v10, v8, s4
	v_ashrrev_i32_e32 v9, 31, v8
	v_add3_u32 v20, s60, v6, v10
	v_lshlrev_b64 v[8:9], 11, v[8:9]
	v_lshl_add_u64 v[6:7], s[2:3], 0, v[6:7]
	v_lshl_add_u64 v[8:9], v[6:7], 0, v[8:9]
	v_mul_f32_e32 v6, v30, v31
	v_mul_f32_e32 v7, v13, v31
	v_mul_f32_e32 v17, v14, v31
	ds_write_b64 v18, v[4:5] offset:224
	v_add_co_u32_e32 v10, vcc, s5, v8
	v_mov_b64_e32 v[0:1], v[152:153]
	v_mov_b64_e32 v[2:3], v[154:155]
	v_mul_f32_e32 v0, v6, v0
	v_mul_f32_e32 v1, v7, v1
	v_mul_f32_e32 v2, v17, v2
	v_mul_f32_e32 v3, v19, v3
	v_cvt_pk_bf16_f32 v0, v0, v1
	v_cvt_pk_bf16_f32 v1, v2, v3
	ds_write_b64 v18, v[0:1] offset:240
	s_waitcnt lgkmcnt(0)
	ds_read_b128 v[96:99], v20
	ds_read_b128 v[100:103], v20 offset:1088
	ds_read_b128 v[104:107], v20 offset:2176
	ds_read_b128 v[108:111], v20 offset:3264
	ds_read_b128 v[112:115], v20 offset:4352
	ds_read_b128 v[116:119], v20 offset:5440
	ds_read_b128 v[120:123], v20 offset:6528
	ds_read_b128 v[124:127], v20 offset:7616
	v_addc_co_u32_e32 v11, vcc, 0, v9, vcc
	s_waitcnt lgkmcnt(7)
	global_store_dwordx4 v[8:9], v[96:99], off
	s_waitcnt lgkmcnt(6)
	global_store_dwordx4 v[10:11], v[100:103], off
	v_add_co_u32_e32 v12, vcc, s12, v8
	s_nop 1
	v_addc_co_u32_e32 v13, vcc, 0, v9, vcc
	v_add_co_u32_e32 v14, vcc, 0x6000, v8
	s_nop 1
	v_addc_co_u32_e32 v15, vcc, 0, v9, vcc
	s_waitcnt lgkmcnt(5)
	global_store_dwordx4 v[12:13], v[104:107], off
	s_waitcnt lgkmcnt(4)
	global_store_dwordx4 v[14:15], v[108:111], off
	v_add_co_u32_e32 v16, vcc, 0x8000, v8
	s_nop 1
	v_addc_co_u32_e32 v17, vcc, 0, v9, vcc
	v_add_co_u32_e32 v18, vcc, 0xa000, v8
	s_nop 1
	v_addc_co_u32_e32 v19, vcc, 0, v9, vcc
	s_waitcnt lgkmcnt(3)
	global_store_dwordx4 v[16:17], v[112:115], off
	s_waitcnt lgkmcnt(2)
	global_store_dwordx4 v[18:19], v[116:119], off
	v_add_co_u32_e32 v10, vcc, 0xc000, v8
	s_nop 1
	v_addc_co_u32_e32 v11, vcc, 0, v9, vcc
	v_add_co_u32_e32 v8, vcc, 0xe000, v8
	s_nop 1
	v_addc_co_u32_e32 v9, vcc, 0, v9, vcc
	s_waitcnt lgkmcnt(1)
	global_store_dwordx4 v[10:11], v[120:123], off
	s_waitcnt lgkmcnt(0)
	global_store_dwordx4 v[8:9], v[124:127], off
	s_branch .LBB0_839
